# FFN2 processes the most recently written activation tiles first (Infinity Cache reuse)
# speedup vs baseline: 1.0003x; 1.0003x over previous
.LBB0_767:
	s_ashr_i32 s18, s21, 3
	s_add_i32 s18, s23, s18
	s_lshr_b32 s21, s18, 5
	s_xor_b32 s21, s21, 2
	s_and_b32 s18, s18, 31
	s_lshl_b32 s21, s21, 2
	s_and_b32 s19, s18, 3
	s_add_i32 s58, s21, s19
	s_lshr_b32 s86, s18, 2

.LBB0_779:
	s_ashr_i32 s20, s22, 3
	s_add_i32 s20, s28, s20
	s_ashr_i32 s21, s20, 31
	s_lshr_b32 s21, s21, 27
	s_add_i32 s21, s20, s21
	s_ashr_i32 s22, s21, 5
	s_xor_b32 s22, s22, 2
	s_lshl_b32 s22, s22, 2
	s_sub_i32 s23, 0x80, s22
	s_min_i32 s23, s23, 4
	s_abs_i32 s28, s23
	v_cvt_f32_u32_e32 v0, s28
	s_sub_i32 s40, 0, s28
	s_andn2_b32 s21, s21, 31
	s_sub_i32 s20, s20, s21
	v_rcp_iflag_f32_e32 v0, v0
	s_abs_i32 s21, s20
	s_xor_b32 s29, s20, s23
	s_ashr_i32 s29, s29, 31
	v_mul_f32_e32 v0, 0x4f7ffffe, v0
	v_cvt_u32_f32_e32 v0, v0
	s_nop 0
	v_readfirstlane_b32 s41, v0
	s_mul_i32 s40, s40, s41
	s_mul_hi_u32 s40, s41, s40
	s_add_i32 s41, s41, s40
	s_mul_hi_u32 s40, s21, s41
	s_mul_i32 s41, s40, s28
	s_sub_i32 s21, s21, s41
	s_add_i32 s51, s40, 1
	s_sub_i32 s41, s21, s28
	s_cmp_ge_u32 s21, s28
	s_cselect_b32 s40, s51, s40
	s_cselect_b32 s21, s41, s21
	s_add_i32 s41, s40, 1
	s_cmp_ge_u32 s21, s28
	s_cselect_b32 s21, s41, s40
	s_xor_b32 s21, s21, s29
	s_sub_i32 s51, s21, s29
	s_mul_i32 s21, s51, s23
	s_sub_i32 s20, s20, s21
	s_add_i32 s52, s22, s20
